# strategy 7: v_pk_mul_f32 decay multiplies beside the scan-loop MFMAs split into scalar v_mul_f32 pairs (bit-identical), on top of v9
# baseline (speedup 1.0000x reference)
; #define LAS __attribute__((address_space(3)))
; __device__ __forceinline__ f32x16 mfma32(bf16x8 a, bf16x8 b, f32x16 c) { return __builtin_amdgcn_mfma_f32_32x32x16_bf16(a, b, c, 0, 0, 0); }
; #define BAR_L() do { asm volatile("s_waitcnt lgkmcnt(0)" ::: "memory"); __builtin_amdgcn_s_barrier(); asm volatile("" ::: "memory"); } while (0)
; __device__ __forceinline__ void gla_scan_item(Frame& F, const int sitem) {
;     ...
;         { const ldsp xw = Xs + w * 8192 + lane * 16;
; #pragma unroll
;           for (int tt = 0; tt < 2; ++tt)
; #pragma unroll
;             for (int g4 = 0; g4 < 4; ++g4) *(LAS f32x4*)(xw + tt * 4096 + g4 * 1024) = (f32x4){oT[tt][4 * g4], oT[tt][4 * g4 + 1], oT[tt][4 * g4 + 2], oT[tt][4 * g4 + 3]}; }
; #pragma unroll
;         for (int kt = 0; kt < 2; ++kt) {
; #pragma unroll
;             for (int g = 0; g < 4; ++g) { const f32x4 dd = *(const LAS f32x4*)(Dc + (dk0 + 32 * kt + 8 * g + 4 * h) * 4);
;                 S[kt][4 * g] *= dd.x; S[kt][4 * g + 1] *= dd.y; S[kt][4 * g + 2] *= dd.z; S[kt][4 * g + 3] *= dd.w; }
; #pragma unroll
;             for (int sp = 0; sp < 4; ++sp) { const bf16x8 kf = *(const LAS bf16x8*)(Kt + (dk0 + 32 * kt + r) * TP + (16 * sp + 8 * h) * 2); S[kt] = mfma32(kf, vf[sp], S[kt]); }
;         }
;         BAR_L();
;         {
;           const int tt = dkq >> 1;
;           bf16* ob = ORAW + ((size_t)b * SEQ + n * 64 + 32 * tt + 4 * h) * 1536 + hh * 384 + sixth * 64 + 32 * dvs + r;
; #pragma unroll
;           for (int gg = 0; gg < 2; ++gg) { const int g4 = 2 * (dkq & 1) + gg; const ldsp xr = Xs + dvs * 8192 + tt * 4096 + g4 * 1024 + lane * 16;
;               const f32x4 p0 = *(const LAS f32x4*)(xr), p1 = *(const LAS f32x4*)(xr + 2 * 8192), p2 = *(const LAS f32x4*)(xr + 4 * 8192), p3 = *(const LAS f32x4*)(xr + 6 * 8192);
;               const f32x4 sm = (p0 + p1) + (p2 + p3);
; #pragma unroll
;               for (int i = 0; i < 4; ++i) ob[(size_t)(i + 8 * g4) * 1536] = (bf16)(pk2(sm[i], 0.f) & 0xffff); } }
.LBB0_710:
	s_nop 8
	v_add_u32_e32 v48, s9, v156
	ds_write_b128 v48, v[32:35]
	ds_write_b128 v48, v[36:39] offset:1024
	ds_write_b128 v48, v[40:43] offset:2048
	ds_write_b128 v48, v[44:47] offset:3072
	ds_write_b128 v48, v[64:67] offset:4096
	ds_write_b128 v48, v[68:71] offset:5120
	ds_write_b128 v48, v[72:75] offset:6144
	ds_write_b128 v48, v[76:79] offset:7168
	ds_read_b128 v[32:35], v164 offset:96
	ds_read_b128 v[36:39], v164 offset:64
	ds_read_b128 v[40:43], v164 offset:32
	ds_read_b128 v[44:47], v164
	ds_read_b128 v[48:51], v165 offset:33792
	s_waitcnt lgkmcnt(0)
	v_mul_f32_e32 v28, v28, v32
	v_mul_f32_e32 v29, v29, v33
	v_mul_f32_e32 v24, v24, v36
	v_mul_f32_e32 v25, v25, v37
	v_mul_f32_e32 v20, v20, v40
	v_mul_f32_e32 v21, v21, v41
	v_mul_f32_e32 v30, v30, v34
	v_mul_f32_e32 v31, v31, v35
	v_mul_f32_e32 v26, v26, v38
	v_mul_f32_e32 v27, v27, v39
	v_mul_f32_e32 v22, v22, v42
	v_mul_f32_e32 v23, v23, v43
	v_mul_f32_e32 v18, v18, v46
	v_mul_f32_e32 v19, v19, v47
	v_mul_f32_e32 v16, v16, v44
	v_mul_f32_e32 v17, v17, v45
	ds_read_b128 v[32:35], v165 offset:33824
	v_lshl_add_u64 v[56:57], s[42:43], 0, v[150:151]
	v_mfma_f32_32x32x16_bf16 v[16:31], v[48:51], v[140:143], v[16:31]
	s_add_i32 s44, s44, 4
	v_lshl_add_u64 v[150:151], v[150:151], 0, s[94:95]
	s_cmpk_lg_i32 s44, 0x100
	v_lshl_add_u64 v[152:153], v[152:153], 0, s[96:97]
	s_waitcnt lgkmcnt(0)
	v_mfma_f32_32x32x16_bf16 v[16:31], v[32:35], v[136:139], v[16:31]
	ds_read_b128 v[32:35], v165 offset:33856
	ds_read_b128 v[36:39], v165 offset:33888
	s_waitcnt lgkmcnt(0)
	v_mfma_f32_32x32x16_bf16 v[16:31], v[32:35], v[132:135], v[16:31]
	ds_read_b128 v[32:35], v164 offset:224
	ds_read_b128 v[40:43], v164 offset:192
	ds_read_b128 v[44:47], v164 offset:128
	ds_read_b128 v[48:51], v164 offset:160
	ds_read_b128 v[52:55], v165 offset:38400
	s_waitcnt lgkmcnt(0)
	v_mul_f32_e32 v12, v12, v32
	v_mul_f32_e32 v13, v13, v33
	v_mul_f32_e32 v8, v8, v40
	v_mul_f32_e32 v9, v9, v41
	v_mul_f32_e32 v14, v14, v34
	v_mul_f32_e32 v15, v15, v35
	v_mul_f32_e32 v4, v4, v48
	v_mul_f32_e32 v5, v5, v49
	v_mul_f32_e32 v10, v10, v42
	v_mul_f32_e32 v11, v11, v43
	v_mul_f32_e32 v6, v6, v50
	v_mul_f32_e32 v7, v7, v51
	v_mul_f32_e32 v2, v2, v46
	v_mul_f32_e32 v3, v3, v47
	v_mul_f32_e32 v0, v0, v44
	v_mul_f32_e32 v1, v1, v45
	ds_read_b128 v[32:35], v165 offset:38432
	v_mfma_f32_32x32x16_bf16 v[16:31], v[36:39], v[128:131], v[16:31]
	ds_read_b128 v[36:39], v165 offset:38464
	ds_read_b128 v[40:43], v165 offset:38496
	s_waitcnt lgkmcnt(0)
	s_barrier
	v_mfma_f32_32x32x16_bf16 v[0:15], v[52:55], v[140:143], v[0:15]
	v_add_u32_e32 v52, s10, v157
	s_waitcnt lgkmcnt(0)
	v_mfma_f32_32x32x16_bf16 v[0:15], v[32:35], v[136:139], v[0:15]
	ds_read_b128 v[32:35], v52
	ds_read_b128 v[44:47], v52 offset:16384
	ds_read_b128 v[48:51], v52 offset:32768
	ds_read_b128 v[52:55], v52 offset:49152
	s_waitcnt lgkmcnt(0)
	v_add_f32_e32 v32, v32, v44
	v_mfma_f32_32x32x16_bf16 v[0:15], v[36:39], v[132:135], v[0:15]
	v_add_f32_e32 v36, v48, v52
	v_add_f32_e32 v32, v32, v36
	v_add_co_u32_e32 v36, vcc, s22, v56
	v_cvt_pk_bf16_f32 v32, v32, s0
	s_nop 0
	v_addc_co_u32_e32 v37, vcc, 0, v57, vcc
	flat_store_short v[36:37], v32
	v_add_f32_e32 v32, v33, v45
	v_add_f32_e32 v33, v49, v53
	v_add_f32_e32 v32, v32, v33
	v_cvt_pk_bf16_f32 v32, v32, s0
	flat_store_short v[36:37], v32 offset:3072
	v_add_f32_e32 v32, v34, v46
	v_add_f32_e32 v33, v50, v54
	v_add_f32_e32 v32, v32, v33
	v_cvt_pk_bf16_f32 v34, v32, s0
	v_add_co_u32_e32 v32, vcc, s23, v56
	v_add_u32_e32 v48, s11, v157
	s_nop 0
	v_addc_co_u32_e32 v33, vcc, 0, v57, vcc
	flat_store_short v[32:33], v34 offset:2048
	v_add_f32_e32 v32, v35, v47
	v_add_f32_e32 v33, v51, v55
	v_add_f32_e32 v32, v32, v33
	v_cvt_pk_bf16_f32 v34, v32, s0
	v_add_co_u32_e32 v32, vcc, s24, v56
	v_mfma_f32_32x32x16_bf16 v[0:15], v[40:43], v[128:131], v[0:15]
	s_nop 0
	v_addc_co_u32_e32 v33, vcc, 0, v57, vcc
	flat_store_short v[32:33], v34 offset:1024
	ds_read_b128 v[32:35], v48
	ds_read_b128 v[36:39], v48 offset:16384
	ds_read_b128 v[44:47], v48 offset:32768
	ds_read_b128 v[48:51], v48 offset:49152
	v_add_co_u32_e32 v40, vcc, s25, v56
	s_waitcnt lgkmcnt(0)
	v_add_f32_e32 v32, v32, v36
	v_addc_co_u32_e32 v41, vcc, 0, v57, vcc
	v_add_f32_e32 v36, v44, v48
	v_add_f32_e32 v32, v32, v36
	v_cvt_pk_bf16_f32 v32, v32, s0
	flat_store_short v[40:41], v32
	v_add_f32_e32 v32, v33, v37
	v_add_f32_e32 v33, v45, v49
	v_add_f32_e32 v32, v32, v33
	v_cvt_pk_bf16_f32 v32, v32, s0
	flat_store_short v[40:41], v32 offset:3072
	v_add_f32_e32 v32, v34, v38
	v_add_f32_e32 v33, v46, v50
	v_add_f32_e32 v32, v32, v33
	v_cvt_pk_bf16_f32 v34, v32, s0
	v_add_co_u32_e32 v32, vcc, s16, v56
	s_nop 1
	v_addc_co_u32_e32 v33, vcc, 0, v57, vcc
	flat_store_short v[32:33], v34 offset:2048
	v_add_f32_e32 v32, v35, v39
	v_add_f32_e32 v33, v47, v51
	v_add_f32_e32 v32, v32, v33
	v_cvt_pk_bf16_f32 v34, v32, s0
	v_add_co_u32_e32 v32, vcc, s17, v56
	s_nop 1
	v_addc_co_u32_e32 v33, vcc, 0, v57, vcc
	flat_store_short v[32:33], v34 offset:1024
	s_cbranch_scc0 .LBB0_728
